# global attention loop: max3 row-max without canonicalizing self-max, softmax/PV section rewritten (in-place exp, scalar adds, V fragments prefetched)
# speedup vs baseline: 1.0231x; 1.0231x over previous
; #define LAS __attribute__((address_space(3)))
; DI unsigned pack2(float lo, float hi) { f32x2 v = {lo, hi}; bf16x2_t b = __builtin_convertvector(v, bf16x2_t); return __builtin_bit_cast(unsigned, b); }
; #define MFMA32(a, b, c) __builtin_amdgcn_mfma_f32_32x32x16_bf16((a), (b), (c), 0, 0, 0)
; DI float fast_exp2(float x) { return __builtin_amdgcn_exp2f(x); }
; template <bool FIRST, bool MASKED>
; DI void attn2_step(f32x16 (&o)[2][2], float (&m_ref)[2], float (&lsum)[2], const bf16x8 (&qf)[2][4], const lchar* Kl, const lchar* Vl, int lane, int kp0, int qw0, float m_init, float l0) {
;     ...
;     bf16x8 pf[2][4];
; #pragma unroll
;     for (int q = 0; q < 2; ++q) {
;         float ps = 0.f;
; #pragma unroll
;         for (int kt = 0; kt < 2; ++kt)
; #pragma unroll
;             for (int i = 0; i < 16; ++i) { const float pv = fast_exp2(sc[q][kt][i]); sc[q][kt][i] = pv; ps += pv; }
;         lsum[q] += ps;
; #pragma unroll
;         for (int s = 0; s < 4; ++s) {
;             u32x4 w;
;             const int kt = s >> 1, b = 8 * (s & 1);
;             w.x = pack2(sc[q][kt][b + 0], sc[q][kt][b + 1]); w.y = pack2(sc[q][kt][b + 2], sc[q][kt][b + 3]);
;             w.z = pack2(sc[q][kt][b + 4], sc[q][kt][b + 5]); w.w = pack2(sc[q][kt][b + 6], sc[q][kt][b + 7]);
;             pf[q][s] = __builtin_bit_cast(bf16x8, w);
;         }
;     }
;     {
;         const int qq = (lane & 15) >> 2, pp = lane & 3, g16 = (lane >> 4) & 1;
;         const lchar* vb = Vl + (4 * h + qq) * VSTR + (16 * g16 + 4 * pp) * 2;
; #pragma unroll
;         for (int s = 0; s < 4; ++s)
; #pragma unroll
;             for (int dt = 0; dt < 2; ++dt) {
;                 const s16x4 lo = __builtin_amdgcn_ds_read_tr16_b64_v4i16((LAS s16x4*)(vb + (16 * s) * VSTR + dt * 64));
;                 const s16x4 hi = __builtin_amdgcn_ds_read_tr16_b64_v4i16((LAS s16x4*)(vb + (16 * s + 8) * VSTR + dt * 64));
;                 const bf16x8 vf = __builtin_shufflevector(lo, hi, 0, 1, 2, 3, 4, 5, 6, 7);
; #pragma unroll
;                 for (int q = 0; q < 2; ++q) o[q][dt] = MFMA32(vf, pf[q][s], o[q][dt]);
;             }
;     }
.LBB0_191:
	v_exp_f32_e32 v112, v112
	v_exp_f32_e32 v113, v113
	v_exp_f32_e32 v114, v114
	v_exp_f32_e32 v115, v115
	v_add_f32_e32 v240, v112, v114
	v_add_f32_e32 v241, v113, v115
	v_exp_f32_e32 v116, v116
	v_exp_f32_e32 v117, v117
	v_exp_f32_e32 v118, v118
	v_exp_f32_e32 v119, v119
	v_add_f32_e32 v240, v240, v116
	v_add_f32_e32 v241, v241, v117
	v_add_f32_e32 v240, v240, v118
	v_add_f32_e32 v241, v241, v119
	v_cvt_pk_bf16_f32 v112, v112, v113
	v_cvt_pk_bf16_f32 v113, v114, v115
	v_cvt_pk_bf16_f32 v114, v116, v117
	v_cvt_pk_bf16_f32 v115, v118, v119
	v_exp_f32_e32 v96, v96
	v_exp_f32_e32 v97, v97
	v_exp_f32_e32 v98, v98
	v_exp_f32_e32 v99, v99
	v_mfma_f32_32x32x16_bf16 v[32:47], v[208:211], v[112:115], v[32:47]
	v_add_f32_e32 v242, v96, v98
	v_add_f32_e32 v243, v97, v99
	v_exp_f32_e32 v100, v100
	v_exp_f32_e32 v101, v101
	v_exp_f32_e32 v102, v102
	v_exp_f32_e32 v103, v103
	v_add_f32_e32 v242, v242, v100
	v_add_f32_e32 v243, v243, v101
	v_mfma_f32_32x32x16_bf16 v[48:63], v[212:215], v[112:115], v[48:63]
	v_add_f32_e32 v242, v242, v102
	v_add_f32_e32 v243, v243, v103
	v_cvt_pk_bf16_f32 v96, v96, v97
	v_cvt_pk_bf16_f32 v97, v98, v99
	v_cvt_pk_bf16_f32 v98, v100, v101
	v_cvt_pk_bf16_f32 v99, v102, v103
	v_exp_f32_e32 v120, v120
	v_exp_f32_e32 v121, v121
	v_exp_f32_e32 v122, v122
	v_exp_f32_e32 v123, v123
	v_mfma_f32_32x32x16_bf16 v[16:31], v[208:211], v[96:99], v[16:31]
	v_add_f32_e32 v240, v240, v120
	v_add_f32_e32 v241, v241, v121
	v_exp_f32_e32 v124, v124
	v_exp_f32_e32 v125, v125
	v_add_f32_e32 v240, v240, v122
	v_add_f32_e32 v241, v241, v123
	v_exp_f32_e32 v126, v126
	v_exp_f32_e32 v127, v127
	v_add_f32_e32 v240, v240, v124
	v_add_f32_e32 v241, v241, v125
	v_mfma_f32_32x32x16_bf16 v[0:15], v[212:215], v[96:99], v[0:15]
	v_add_f32_e32 v240, v240, v126
	v_add_f32_e32 v241, v241, v127
	v_cvt_pk_bf16_f32 v120, v120, v121
	v_cvt_pk_bf16_f32 v121, v122, v123
	v_cvt_pk_bf16_f32 v122, v124, v125
	v_cvt_pk_bf16_f32 v123, v126, v127
	v_exp_f32_e32 v104, v104
	v_exp_f32_e32 v105, v105
	v_exp_f32_e32 v106, v106
	v_exp_f32_e32 v107, v107
	v_mfma_f32_32x32x16_bf16 v[32:47], v[216:219], v[120:123], v[32:47]
	v_add_f32_e32 v242, v242, v104
	v_add_f32_e32 v243, v243, v105
	v_exp_f32_e32 v108, v108
	v_exp_f32_e32 v109, v109
	v_add_f32_e32 v242, v242, v106
	v_add_f32_e32 v243, v243, v107
	v_exp_f32_e32 v110, v110
	v_exp_f32_e32 v111, v111
	v_add_f32_e32 v242, v242, v108
	v_add_f32_e32 v243, v243, v109
	v_mfma_f32_32x32x16_bf16 v[48:63], v[220:223], v[120:123], v[48:63]
	v_add_f32_e32 v242, v242, v110
	v_add_f32_e32 v243, v243, v111
	v_cvt_pk_bf16_f32 v104, v104, v105
	v_cvt_pk_bf16_f32 v105, v106, v107
	v_cvt_pk_bf16_f32 v106, v108, v109
	v_cvt_pk_bf16_f32 v107, v110, v111
	v_exp_f32_e32 v80, v80
	v_exp_f32_e32 v81, v81
	v_exp_f32_e32 v82, v82
	v_exp_f32_e32 v83, v83
	v_mfma_f32_32x32x16_bf16 v[16:31], v[216:219], v[104:107], v[16:31]
	v_add_f32_e32 v240, v240, v80
	v_add_f32_e32 v241, v241, v81
	v_exp_f32_e32 v84, v84
	v_exp_f32_e32 v85, v85
	v_add_f32_e32 v240, v240, v82
	v_add_f32_e32 v241, v241, v83
	v_exp_f32_e32 v86, v86
	v_exp_f32_e32 v87, v87
	v_add_f32_e32 v240, v240, v84
	v_add_f32_e32 v241, v241, v85
	v_mfma_f32_32x32x16_bf16 v[0:15], v[220:223], v[104:107], v[0:15]
	v_add_f32_e32 v240, v240, v86
	v_add_f32_e32 v241, v241, v87
	v_cvt_pk_bf16_f32 v80, v80, v81
	v_cvt_pk_bf16_f32 v81, v82, v83
	v_cvt_pk_bf16_f32 v82, v84, v85
	v_cvt_pk_bf16_f32 v83, v86, v87
	v_exp_f32_e32 v64, v64
	v_exp_f32_e32 v65, v65
	v_exp_f32_e32 v66, v66
	v_exp_f32_e32 v67, v67
	s_waitcnt lgkmcnt(0)
	v_mfma_f32_32x32x16_bf16 v[32:47], v[224:227], v[80:83], v[32:47]
	v_add_f32_e32 v242, v242, v64
	v_add_f32_e32 v243, v243, v65
	v_exp_f32_e32 v68, v68
	v_exp_f32_e32 v69, v69
	v_add_f32_e32 v242, v242, v66
	v_add_f32_e32 v243, v243, v67
	v_exp_f32_e32 v70, v70
	v_exp_f32_e32 v71, v71
	v_add_f32_e32 v242, v242, v68
	v_add_f32_e32 v243, v243, v69
	v_mfma_f32_32x32x16_bf16 v[48:63], v[228:231], v[80:83], v[48:63]
	v_add_f32_e32 v242, v242, v70
	v_add_f32_e32 v243, v243, v71
	v_cvt_pk_bf16_f32 v64, v64, v65
	v_cvt_pk_bf16_f32 v65, v66, v67
	v_cvt_pk_bf16_f32 v66, v68, v69
	v_cvt_pk_bf16_f32 v67, v70, v71
	v_exp_f32_e32 v88, v88
	v_exp_f32_e32 v89, v89
	v_exp_f32_e32 v90, v90
	v_exp_f32_e32 v91, v91
	v_mfma_f32_32x32x16_bf16 v[16:31], v[224:227], v[64:67], v[16:31]
	v_add_f32_e32 v240, v240, v88
	v_add_f32_e32 v241, v241, v89
	v_exp_f32_e32 v92, v92
	v_exp_f32_e32 v93, v93
	v_add_f32_e32 v240, v240, v90
	v_add_f32_e32 v241, v241, v91
	v_exp_f32_e32 v94, v94
	v_exp_f32_e32 v95, v95
	v_add_f32_e32 v240, v240, v92
	v_add_f32_e32 v241, v241, v93
	v_mfma_f32_32x32x16_bf16 v[0:15], v[228:231], v[64:67], v[0:15]
	v_add_f32_e32 v240, v240, v94
	v_add_f32_e32 v241, v241, v95
	v_cvt_pk_bf16_f32 v88, v88, v89
	v_cvt_pk_bf16_f32 v89, v90, v91
	v_cvt_pk_bf16_f32 v90, v92, v93
	v_cvt_pk_bf16_f32 v91, v94, v95
	v_exp_f32_e32 v72, v72
	v_exp_f32_e32 v73, v73
	v_exp_f32_e32 v74, v74
	v_exp_f32_e32 v75, v75
	v_mfma_f32_32x32x16_bf16 v[32:47], v[232:235], v[88:91], v[32:47]
	v_add_f32_e32 v242, v242, v72
	v_add_f32_e32 v243, v243, v73
	v_exp_f32_e32 v76, v76
	v_exp_f32_e32 v77, v77
	v_add_f32_e32 v242, v242, v74
	v_add_f32_e32 v243, v243, v75
	v_exp_f32_e32 v78, v78
	v_exp_f32_e32 v79, v79
	v_add_f32_e32 v242, v242, v76
	v_add_f32_e32 v243, v243, v77
	v_mfma_f32_32x32x16_bf16 v[48:63], v[236:239], v[88:91], v[48:63]
	v_add_f32_e32 v242, v242, v78
	v_add_f32_e32 v243, v243, v79
	v_cvt_pk_bf16_f32 v72, v72, v73
	v_cvt_pk_bf16_f32 v73, v74, v75
	v_cvt_pk_bf16_f32 v74, v76, v77
	v_cvt_pk_bf16_f32 v75, v78, v79
	s_add_i32 s22, s22, 1
	v_add_f32_e32 v240, v240, v241
	v_add_f32_e32 v242, v242, v243
	s_cmpk_lg_i32 s22, 0x45
	v_add_f32_e32 v183, v183, v240
	v_add_f32_e32 v182, v182, v242
	s_waitcnt lgkmcnt(0)
	s_barrier
	v_mfma_f32_32x32x16_bf16 v[16:31], v[232:235], v[72:75], v[16:31]
	v_mfma_f32_32x32x16_bf16 v[0:15], v[236:239], v[72:75], v[0:15]
	s_cbranch_scc0 .LBB0_194
; template <bool FIRST, bool MASKED>
; DI void attn2_step(f32x16 (&o)[2][2], float (&m_ref)[2], float (&lsum)[2], const bf16x8 (&qf)[2][4], const lchar* Kl, const lchar* Vl, int lane, int kp0, int qw0, float m_init, float l0) {
;     ...
;     bf16x8 kf[4][2];
; #pragma unroll
;     for (int ks = 0; ks < 4; ++ks)
; #pragma unroll
;         for (int kt = 0; kt < 2; ++kt) kf[ks][kt] = *(const LAS bf16x8*)(Kl + (32 * kt + l31) * KSTR + ks * 32 + h * 16);
;     f32x16 sc[2][2];
; #pragma unroll
;     for (int q = 0; q < 2; ++q) {
;         const float init = FIRST ? opaque0() : -m_ref[q];
; #pragma unroll
;         for (int kt = 0; kt < 2; ++kt)
; #pragma unroll
;             for (int i = 0; i < 16; ++i) sc[q][kt][i] = init;
; #pragma unroll
;         for (int ks = 0; ks < 4; ++ks)
; #pragma unroll
;             for (int kt = 0; kt < 2; ++kt) sc[q][kt] = MFMA32(kf[ks][kt], qf[q][ks], sc[q][kt]);
;     }
;     if (MASKED && kp0 >= 0 && !(kp0 >= qw0 + 63 - 128 && kp0 + 63 <= qw0 + 128)) {
; #pragma unroll
;         for (int q = 0; q < 2; ++q) {
;             const int qpos = qw0 + q * 32 + l31;
; #pragma unroll
;             for (int kt = 0; kt < 2; ++kt)
; #pragma unroll
;                 for (int i = 0; i < 16; ++i) {
;                     const int diff = qpos - (kp0 + 32 * kt + crow(i, h));
;                     if (diff > 128 || diff < -128) sc[q][kt][i] = -1e30f;
;                 }
;         }
;     }
;     float mx[2];
; #pragma unroll
;     for (int q = 0; q < 2; ++q) {
;         float m = fmaxf(sc[q][0][0], sc[q][1][0]);
; #pragma unroll
;         for (int i = 1; i < 16; ++i) m = fmaxf(m, fmaxf(sc[q][0][i], sc[q][1][i]));
;         mx[q] = fmaxf(m, shx(m, 32, lane));
;     }
;     if (FIRST) {
; #pragma unroll
;         for (int q = 0; q < 2; ++q) {
;             m_ref[q] = fmaxf(m_init, mx[q]);
;             lsum[q] = (h == 0) ? l0 * fast_exp2(m_init - m_ref[q]) : 0.f;
; #pragma unroll
;             for (int kt = 0; kt < 2; ++kt)
; #pragma unroll
;                 for (int i = 0; i < 16; ++i) sc[q][kt][i] -= m_ref[q];
;         }
;     } else if (__builtin_amdgcn_ballot_w64(fmaxf(mx[0], mx[1]) > ATT_THR) != 0ull) {
; template <bool MASKED> ...
;     ...
;     for (int it = 1; it < ntiles; ++it) {
;         *(LAS u32x4*)(Kbase + ((it + 1) & 1) * KV_K + koff) = rk; *(LAS u32x4*)(Vbase + ((it + 1) & 1) * VB + voff) = rv;
;         const int i2 = min(it + 2, ntiles - 1);
.LBB0_192:
	s_and_b32 s26, s22, 1
	s_mul_i32 s27, s26, 0x2400
	s_add_i32 s23, s22, -1
	v_add_u32_e32 v64, s27, v176
	s_mulk_i32 s26, 0x3000
	s_waitcnt vmcnt(1)
	ds_write_b128 v64, v[162:165]
	v_add_u32_e32 v64, s26, v178
	s_min_i32 s26, s23, 0x41
	s_cmp_lt_u32 s23, 62
	s_cselect_b32 s27, 2, 0xffffffc2
	s_cselect_b32 s36, s1, s2
	s_and_b32 s23, s23, 1
	s_mul_i32 s37, s23, 0x2400
	s_waitcnt vmcnt(0)
	ds_write_b128 v64, v[166:169] offset:18432
	v_or_b32_e32 v64, s37, v128
	v_add_u32_e32 v65, v64, v179
	v_add_u32_e32 v64, v64, v189
	ds_read_b128 v[162:165], v65
	ds_read_b128 v[192:195], v65 offset:32
	ds_read_b128 v[208:211], v64
	ds_read_b128 v[212:215], v64 offset:32
	s_add_i32 s27, s27, s26
	v_xor_b32_e32 v80, 0x80000000, v181
	s_lshl_b32 s26, s27, 6
	v_mov_b32_e32 v81, v80
	v_mov_b32_e32 v82, v80
	v_mov_b32_e32 v83, v80
	v_mov_b32_e32 v84, v80
	v_mov_b32_e32 v85, v80
	v_mov_b32_e32 v86, v80
	v_mov_b32_e32 v87, v80
	v_mov_b32_e32 v88, v80
	v_mov_b32_e32 v89, v80
	v_mov_b32_e32 v90, v80
	v_mov_b32_e32 v91, v80
	v_mov_b32_e32 v92, v80
	v_mov_b32_e32 v93, v80
	v_mov_b32_e32 v94, v80
	v_mov_b32_e32 v95, v80
	ds_read_b128 v[216:219], v65 offset:64
	ds_read_b128 v[220:223], v65 offset:96
	ds_read_b128 v[224:227], v64 offset:64
	ds_read_b128 v[228:231], v64 offset:96
	s_add_i32 s26, s26, s36
	v_xor_b32_e32 v64, 0x80000000, v180
	s_waitcnt lgkmcnt(7)
	v_mfma_f32_32x32x16_bf16 v[112:127], v[162:165], v[130:133], v[80:95]
	v_add_u32_e32 v166, s26, v188
	v_mov_b32_e32 v65, v64
	v_mov_b32_e32 v66, v64
	v_mov_b32_e32 v67, v64
	v_mov_b32_e32 v68, v64
	v_mov_b32_e32 v69, v64
	v_mov_b32_e32 v70, v64
	s_waitcnt lgkmcnt(5)
	v_mfma_f32_32x32x16_bf16 v[80:95], v[208:211], v[130:133], v[80:95]
	v_mov_b32_e32 v71, v64
	v_mov_b32_e32 v72, v64
	v_mov_b32_e32 v73, v64
	v_mov_b32_e32 v74, v64
	v_mov_b32_e32 v75, v64
	v_mov_b32_e32 v76, v64
	v_mov_b32_e32 v77, v64
	v_mov_b32_e32 v78, v64
	v_mov_b32_e32 v79, v64
	v_mfma_f32_32x32x16_bf16 v[112:127], v[192:195], v[134:137], v[112:127]
	s_nop 0
	v_mfma_f32_32x32x16_bf16 v[96:111], v[162:165], v[146:149], v[64:79]
	v_mad_i64_i32 v[162:163], s[26:27], s30, v166, 0
	v_lshlrev_b64 v[162:163], 1, v[162:163]
	v_lshl_add_u64 v[164:165], v[184:185], 0, v[162:163]
	v_lshl_add_u64 v[166:167], v[186:187], 0, v[162:163]
	global_load_dwordx4 v[162:165], v[164:165], off
	s_nop 0
	global_load_dwordx4 v[166:169], v[166:167], off
	s_mov_b32 s26, 0x41000000
	s_waitcnt lgkmcnt(4)
	v_mfma_f32_32x32x16_bf16 v[80:95], v[212:215], v[134:137], v[80:95]
	s_waitcnt lgkmcnt(3)
	v_mfma_f32_32x32x16_bf16 v[112:127], v[216:219], v[138:141], v[112:127]
	s_waitcnt lgkmcnt(1)
	v_mfma_f32_32x32x16_bf16 v[80:95], v[224:227], v[138:141], v[80:95]
	v_mfma_f32_32x32x16_bf16 v[64:79], v[208:211], v[146:149], v[64:79]
	v_mfma_f32_32x32x16_bf16 v[112:127], v[220:223], v[142:145], v[112:127]
	s_waitcnt lgkmcnt(0)
	v_mfma_f32_32x32x16_bf16 v[80:95], v[228:231], v[142:145], v[80:95]
	s_nop 9
	v_max3_f32 v196, v112, v113, v114
	v_max3_f32 v196, v196, v115, v116
	v_mfma_f32_32x32x16_bf16 v[96:111], v[192:195], v[150:153], v[96:111]
	v_max3_f32 v196, v196, v117, v118
	v_max3_f32 v196, v196, v119, v120
	v_max3_f32 v196, v196, v121, v122
	v_mfma_f32_32x32x16_bf16 v[64:79], v[212:215], v[150:153], v[64:79]
	v_max3_f32 v196, v196, v123, v124
	v_max3_f32 v196, v196, v125, v126
	v_max3_f32 v196, v196, v127, v80
	v_mfma_f32_32x32x16_bf16 v[96:111], v[216:219], v[154:157], v[96:111]
	v_max3_f32 v196, v196, v81, v82
	v_max3_f32 v196, v196, v83, v84
	v_max3_f32 v196, v196, v85, v86
	v_mfma_f32_32x32x16_bf16 v[64:79], v[224:227], v[154:157], v[64:79]
	v_max3_f32 v196, v196, v87, v88
	v_max3_f32 v196, v196, v89, v90
	v_max3_f32 v196, v196, v91, v92
	v_mfma_f32_32x32x16_bf16 v[96:111], v[220:223], v[158:161], v[96:111]
	v_max3_f32 v196, v196, v93, v94
	v_max_f32_e32 v192, v196, v95
	v_mfma_f32_32x32x16_bf16 v[64:79], v[228:231], v[158:161], v[64:79]
	ds_bpermute_b32 v193, v177, v192
	s_mulk_i32 s23, 0x3000
	v_or_b32_e32 v244, s23, v191
	ds_read_b64_tr_b16 v[208:209], v244 offset:18432
	ds_read_b64_tr_b16 v[210:211], v244 offset:19968
	ds_read_b64_tr_b16 v[212:213], v244 offset:18496
	ds_read_b64_tr_b16 v[214:215], v244 offset:20032
	ds_read_b64_tr_b16 v[216:217], v244 offset:21504
	ds_read_b64_tr_b16 v[218:219], v244 offset:23040
	ds_read_b64_tr_b16 v[220:221], v244 offset:21568
	ds_read_b64_tr_b16 v[222:223], v244 offset:23104
	v_max3_f32 v194, v96, v97, v98
	v_max3_f32 v194, v194, v99, v100
	v_max3_f32 v194, v194, v101, v102
	v_max3_f32 v194, v194, v103, v104
	v_max3_f32 v194, v194, v105, v106
	v_max3_f32 v194, v194, v107, v108
	v_max3_f32 v194, v194, v109, v110
	v_max3_f32 v194, v194, v111, v64
	v_max3_f32 v194, v194, v65, v66
	v_max3_f32 v194, v194, v67, v68
	v_max3_f32 v194, v194, v69, v70
	v_max3_f32 v194, v194, v71, v72
	v_max3_f32 v194, v194, v73, v74
	v_max3_f32 v194, v194, v75, v76
	v_max3_f32 v194, v194, v77, v78
	v_max_f32_e32 v194, v194, v79
	ds_bpermute_b32 v195, v177, v194
	s_waitcnt lgkmcnt(9)
	v_max_f32_e32 v193, v192, v193
	s_waitcnt lgkmcnt(0)
	v_max_f32_e32 v192, v194, v195
	ds_read_b64_tr_b16 v[224:225], v244 offset:24576
	ds_read_b64_tr_b16 v[226:227], v244 offset:26112
	ds_read_b64_tr_b16 v[228:229], v244 offset:24640
	ds_read_b64_tr_b16 v[230:231], v244 offset:26176
	ds_read_b64_tr_b16 v[232:233], v244 offset:27648
	ds_read_b64_tr_b16 v[234:235], v244 offset:29184
	ds_read_b64_tr_b16 v[236:237], v244 offset:27712
	ds_read_b64_tr_b16 v[238:239], v244 offset:29248
	v_max_f32_e32 v194, v193, v192
	v_cmp_lt_f32_e32 vcc, s26, v194
	s_cbranch_vccz .LBB0_191
; DI float fast_exp2(float x) { return __builtin_amdgcn_exp2f(x); }
; template <bool FIRST, bool MASKED>
; DI void attn2_step(f32x16 (&o)[2][2], float (&m_ref)[2], float (&lsum)[2], const bf16x8 (&qf)[2][4], const lchar* Kl, const lchar* Vl, int lane, int kp0, int qw0, float m_init, float l0) {
;     ...
;     } else if (__builtin_amdgcn_ballot_w64(fmaxf(mx[0], mx[1]) > ATT_THR) != 0ull) {
; #pragma unroll
;         for (int q = 0; q < 2; ++q) {
;             const float delta = fmaxf(mx[q], 0.f), alpha = fast_exp2(-delta);
; #pragma unroll
;             for (int dt = 0; dt < 2; ++dt)
; #pragma unroll
;                 for (int i = 0; i < 16; ++i) o[q][dt][i] *= alpha;
;             lsum[q] *= alpha;
; #pragma unroll
;             for (int kt = 0; kt < 2; ++kt)
; #pragma unroll
;                 for (int i = 0; i < 16; ++i) sc[q][kt][i] -= delta;
;             m_ref[q] += delta;
;         }
;     }
	v_max_f32_e32 v193, v193, v193
	v_max_f32_e32 v192, v192, v192
	v_max_f32_e32 v194, 0, v193
	v_max_f32_e32 v192, 0, v192
	v_exp_f32_e64 v196, -v194
	v_exp_f32_e64 v200, -v192
	v_pk_add_f32 v[96:97], v[96:97], v[192:193] op_sel_hi:[1,0] neg_lo:[0,1] neg_hi:[0,1]
	v_pk_add_f32 v[98:99], v[98:99], v[192:193] op_sel_hi:[1,0] neg_lo:[0,1] neg_hi:[0,1]
	v_pk_add_f32 v[100:101], v[100:101], v[192:193] op_sel_hi:[1,0] neg_lo:[0,1] neg_hi:[0,1]
	v_pk_mul_f32 v[30:31], v[30:31], v[200:201] op_sel_hi:[1,0]
	v_pk_mul_f32 v[28:29], v[28:29], v[200:201] op_sel_hi:[1,0]
	v_pk_mul_f32 v[26:27], v[26:27], v[200:201] op_sel_hi:[1,0]
	v_pk_mul_f32 v[24:25], v[24:25], v[200:201] op_sel_hi:[1,0]
	v_pk_mul_f32 v[22:23], v[22:23], v[200:201] op_sel_hi:[1,0]
	v_pk_mul_f32 v[20:21], v[20:21], v[200:201] op_sel_hi:[1,0]
	v_pk_mul_f32 v[18:19], v[18:19], v[200:201] op_sel_hi:[1,0]
	v_pk_mul_f32 v[16:17], v[16:17], v[200:201] op_sel_hi:[1,0]
	v_pk_mul_f32 v[14:15], v[14:15], v[200:201] op_sel_hi:[1,0]
	v_pk_mul_f32 v[12:13], v[12:13], v[200:201] op_sel_hi:[1,0]
	v_pk_mul_f32 v[10:11], v[10:11], v[200:201] op_sel_hi:[1,0]
	v_pk_mul_f32 v[8:9], v[8:9], v[200:201] op_sel_hi:[1,0]
	v_pk_mul_f32 v[6:7], v[6:7], v[200:201] op_sel_hi:[1,0]
	v_pk_mul_f32 v[4:5], v[4:5], v[200:201] op_sel_hi:[1,0]
	v_pk_mul_f32 v[2:3], v[2:3], v[200:201] op_sel_hi:[1,0]
	v_pk_mul_f32 v[0:1], v[0:1], v[200:201] op_sel_hi:[1,0]
	v_mov_b32_e32 v201, v196
	v_pk_add_f32 v[102:103], v[102:103], v[192:193] op_sel_hi:[1,0] neg_lo:[0,1] neg_hi:[0,1]
	v_pk_add_f32 v[104:105], v[104:105], v[192:193] op_sel_hi:[1,0] neg_lo:[0,1] neg_hi:[0,1]
	v_pk_add_f32 v[106:107], v[106:107], v[192:193] op_sel_hi:[1,0] neg_lo:[0,1] neg_hi:[0,1]
	v_pk_add_f32 v[108:109], v[108:109], v[192:193] op_sel_hi:[1,0] neg_lo:[0,1] neg_hi:[0,1]
	v_pk_add_f32 v[110:111], v[110:111], v[192:193] op_sel_hi:[1,0] neg_lo:[0,1] neg_hi:[0,1]
	v_pk_add_f32 v[64:65], v[64:65], v[192:193] op_sel_hi:[1,0] neg_lo:[0,1] neg_hi:[0,1]
	v_pk_add_f32 v[66:67], v[66:67], v[192:193] op_sel_hi:[1,0] neg_lo:[0,1] neg_hi:[0,1]
	v_pk_add_f32 v[68:69], v[68:69], v[192:193] op_sel_hi:[1,0] neg_lo:[0,1] neg_hi:[0,1]
	v_pk_add_f32 v[70:71], v[70:71], v[192:193] op_sel_hi:[1,0] neg_lo:[0,1] neg_hi:[0,1]
	v_pk_add_f32 v[72:73], v[72:73], v[192:193] op_sel_hi:[1,0] neg_lo:[0,1] neg_hi:[0,1]
	v_pk_add_f32 v[74:75], v[74:75], v[192:193] op_sel_hi:[1,0] neg_lo:[0,1] neg_hi:[0,1]
	v_pk_add_f32 v[76:77], v[76:77], v[192:193] op_sel_hi:[1,0] neg_lo:[0,1] neg_hi:[0,1]
	v_pk_add_f32 v[78:79], v[78:79], v[192:193] op_sel_hi:[1,0] neg_lo:[0,1] neg_hi:[0,1]
	v_mov_b32_e32 v193, v194
	v_pk_mul_f32 v[46:47], v[46:47], v[196:197] op_sel_hi:[1,0]
	v_pk_mul_f32 v[44:45], v[44:45], v[196:197] op_sel_hi:[1,0]
	v_pk_mul_f32 v[42:43], v[42:43], v[196:197] op_sel_hi:[1,0]
	v_pk_mul_f32 v[40:41], v[40:41], v[196:197] op_sel_hi:[1,0]
	v_pk_mul_f32 v[38:39], v[38:39], v[196:197] op_sel_hi:[1,0]
	v_pk_mul_f32 v[36:37], v[36:37], v[196:197] op_sel_hi:[1,0]
	v_pk_mul_f32 v[34:35], v[34:35], v[196:197] op_sel_hi:[1,0]
	v_pk_mul_f32 v[32:33], v[32:33], v[196:197] op_sel_hi:[1,0]
	v_pk_mul_f32 v[62:63], v[62:63], v[196:197] op_sel_hi:[1,0]
	v_pk_mul_f32 v[60:61], v[60:61], v[196:197] op_sel_hi:[1,0]
	v_pk_mul_f32 v[58:59], v[58:59], v[196:197] op_sel_hi:[1,0]
	v_pk_mul_f32 v[56:57], v[56:57], v[196:197] op_sel_hi:[1,0]
	v_pk_mul_f32 v[54:55], v[54:55], v[196:197] op_sel_hi:[1,0]
	v_pk_mul_f32 v[52:53], v[52:53], v[196:197] op_sel_hi:[1,0]
	v_pk_mul_f32 v[50:51], v[50:51], v[196:197] op_sel_hi:[1,0]
	v_pk_mul_f32 v[48:49], v[48:49], v[196:197] op_sel_hi:[1,0]
	v_pk_add_f32 v[112:113], v[112:113], v[194:195] op_sel_hi:[1,0] neg_lo:[0,1] neg_hi:[0,1]
	v_pk_add_f32 v[114:115], v[114:115], v[194:195] op_sel_hi:[1,0] neg_lo:[0,1] neg_hi:[0,1]
	v_pk_add_f32 v[116:117], v[116:117], v[194:195] op_sel_hi:[1,0] neg_lo:[0,1] neg_hi:[0,1]
	v_pk_add_f32 v[118:119], v[118:119], v[194:195] op_sel_hi:[1,0] neg_lo:[0,1] neg_hi:[0,1]
	v_pk_add_f32 v[120:121], v[120:121], v[194:195] op_sel_hi:[1,0] neg_lo:[0,1] neg_hi:[0,1]
	v_pk_add_f32 v[122:123], v[122:123], v[194:195] op_sel_hi:[1,0] neg_lo:[0,1] neg_hi:[0,1]
	v_pk_add_f32 v[124:125], v[124:125], v[194:195] op_sel_hi:[1,0] neg_lo:[0,1] neg_hi:[0,1]
	v_pk_add_f32 v[126:127], v[126:127], v[194:195] op_sel_hi:[1,0] neg_lo:[0,1] neg_hi:[0,1]
	v_pk_add_f32 v[80:81], v[80:81], v[194:195] op_sel_hi:[1,0] neg_lo:[0,1] neg_hi:[0,1]
	v_pk_add_f32 v[82:83], v[82:83], v[194:195] op_sel_hi:[1,0] neg_lo:[0,1] neg_hi:[0,1]
	v_pk_add_f32 v[84:85], v[84:85], v[194:195] op_sel_hi:[1,0] neg_lo:[0,1] neg_hi:[0,1]
	v_pk_add_f32 v[86:87], v[86:87], v[194:195] op_sel_hi:[1,0] neg_lo:[0,1] neg_hi:[0,1]
	v_pk_add_f32 v[88:89], v[88:89], v[194:195] op_sel_hi:[1,0] neg_lo:[0,1] neg_hi:[0,1]
	v_pk_add_f32 v[90:91], v[90:91], v[194:195] op_sel_hi:[1,0] neg_lo:[0,1] neg_hi:[0,1]
	v_pk_add_f32 v[92:93], v[92:93], v[194:195] op_sel_hi:[1,0] neg_lo:[0,1] neg_hi:[0,1]
	v_pk_add_f32 v[94:95], v[94:95], v[194:195] op_sel_hi:[1,0] neg_lo:[0,1] neg_hi:[0,1]
	v_pk_mul_f32 v[182:183], v[182:183], v[200:201]
	v_pk_add_f32 v[180:181], v[180:181], v[192:193]
	s_branch .LBB0_191
